# removed the pre-arrival LDS-DMA stage issue at barriers 3 and 6 (redundant now that those barriers are split; it delayed the arrival)
# speedup vs baseline: 1.0064x; 1.0004x over previous
; #define SEAM(k) do { if (IN(k) && IN((k) + 1)) { xcd_barrier(xbar); if (REPB > 1) xcd_barrier(xbar); } } while (0)
; __device__ __forceinline__ void xcd_barrier(const XcdBarrier& b) {
;     asm volatile("s_waitcnt vmcnt(0)" ::: "memory");
;     __syncthreads();
;     if (threadIdx.x == 0) {
;         unsigned* bar = b.bar;
;         __builtin_amdgcn_s_waitcnt(0);
;         unsigned nloc = b.st[0], nx = b.st[1];
;         if (nloc == 0u) { xcd_barrier_complete(bar, b.x, nloc, nx); b.st[0] = nloc; b.st[1] = nx; }
; __global__ void __launch_bounds__(512, 2) mega_fwd(Params p) {
;     ...
;     SEAM(3);
;     if (IN(4)) {
;         pg8::Gemm g{H, WinT + (size_t)5120 * 1024, T_TOK, 7168, 1024}; pg8::StaticOrder S; S.init(T_TOK, 7168, G, bid);
;         EpiProjB E{R1, (bf16_t*)(ws + WS_R1 + R1_KA), (bf16_t*)(ws + WS_R1 + R1_VA), R2};
;         for (int rep = 0; rep < REP4; ++rep) pg8::gemm_phase<EpiProjB>(lds, g, S, E);
.LBB0_359:
	s_mov_b32 s99, 0
	s_mov_b32 s100, 0
	s_cmp_gt_i32 s91, 4
	v_readlane_b32 s2, v254, 25
	s_cselect_b64 s[0:1], -1, 0
	v_readlane_b32 s3, v254, 26
	s_and_b64 s[2:3], s[2:3], s[0:1]
	s_andn2_b64 vcc, exec, s[2:3]
	s_cbranch_vccnz .LBB0_409
	s_cmp_eq_u32 s82, 0x100
	s_cselect_b32 s99, 1, 0
	s_waitcnt vmcnt(0)
	s_waitcnt vmcnt(0) lgkmcnt(0)
	s_barrier
	s_mov_b64 s[2:3], exec
	v_readlane_b32 s4, v254, 1
	v_readlane_b32 s5, v254, 2
	s_and_b64 s[4:5], s[2:3], s[4:5]
	s_mov_b64 exec, s[4:5]
	s_cbranch_execz .LBB0_408
	v_readlane_b32 s4, v254, 22
	s_waitcnt vmcnt(0) expcnt(0) lgkmcnt(0)
	s_nop 0
	v_mov_b32_e32 v0, s4
	ds_read_b32 v2, v0
	ds_read_b32 v0, v0 offset:4
	s_waitcnt lgkmcnt(1)
	v_cmp_ne_u32_e32 vcc, 0, v2
	s_cbranch_vccnz .LBB0_376
	v_readlane_b32 s4, v254, 0
	s_mul_i32 s33, s83, s4
	s_add_u32 s4, s88, 0xffc0200
	s_addc_u32 s5, s89, 0
	s_add_u32 s6, s88, 0xffc0400
	s_addc_u32 s7, s89, 0
	s_add_u32 s8, s88, 0xffc0500
	s_addc_u32 s9, s89, 0
	s_add_u32 s10, s88, 0xffc0600
	s_addc_u32 s11, s89, 0
	s_add_u32 s12, s88, 0xffc0700
	s_addc_u32 s13, s89, 0
	s_add_u32 s14, s88, 0xffc0800
	s_addc_u32 s15, s89, 0
	s_add_u32 s16, s88, 0xffc0900
	s_addc_u32 s17, s89, 0
	s_add_u32 s18, s88, 0xffc0a00
	s_addc_u32 s19, s89, 0
	s_add_u32 s20, s88, 0xffc0b00
	s_addc_u32 s21, s89, 0
	s_add_u32 s22, s88, 0xffc0c00
	s_addc_u32 s23, s89, 0
	s_add_u32 s24, s88, 0xffc0d00
	s_addc_u32 s25, s89, 0
	s_add_u32 s26, s88, 0xffc0e00
	s_addc_u32 s27, s89, 0
	s_add_u32 s28, s88, 0xffc0f00
	s_addc_u32 s29, s89, 0
	s_add_u32 s30, s88, 0xffc1000
	s_addc_u32 s31, s89, 0
	s_add_u32 s34, s88, 0xffc1100
	s_addc_u32 s35, s89, 0
	s_add_u32 s36, s88, 0xffc1200
	s_addc_u32 s37, s89, 0
	s_add_u32 s38, s88, 0xffc1300
	s_mul_i32 s33, s33, s82
	s_addc_u32 s39, s89, 0
	s_mov_b32 s46, 1
	v_mov_b32_e32 v16, 0
	s_branch .LBB0_364

; __device__ __forceinline__ void xcd_barrier(const XcdBarrier& b) {
;     asm volatile("s_waitcnt vmcnt(0)" ::: "memory");
;     __syncthreads();
;     if (threadIdx.x == 0) {
;         unsigned* bar = b.bar;
;         __builtin_amdgcn_s_waitcnt(0);
;         unsigned nloc = b.st[0], nx = b.st[1];
;         if (nloc == 0u) { xcd_barrier_complete(bar, b.x, nloc, nx); b.st[0] = nloc; b.st[1] = nx; }
; __global__ void __launch_bounds__(512, 2) mega_fwd(Params p) {
;     ...
;     if (IN(7)) {
;         bf16_t* MG = (bf16_t*)(ws + WS_R1 + R1_MG);
;         pg8::Gemm g0{HM, (const bf16_t*)(ws + WS_WPM), T_TOK, 1024, 1024}; pg8::Gemm g1{ATT, (const bf16_t*)(ws + WS_WPA), T_TOK, 1024, 512};
;         pg8::StaticOrder S; S.init(T_TOK, 1024, G, bid);
;         EpiRatio E0{R2}; EpiMerge2 E1{R2, MG};
;         pg8::gemm_phase2<EpiRatio, EpiMerge2>(lds, g0, g1, S, E0, E1);
.LBB0_703:
	s_mov_b32 s101, 0
	s_mov_b32 s98, 0
	s_cmp_gt_i32 s91, 7
	s_cselect_b64 s[0:1], -1, 0
	s_and_b64 s[2:3], s[8:9], s[0:1]
	s_andn2_b64 vcc, exec, s[2:3]
	s_cbranch_vccnz .LBB0_753
	s_cmp_eq_u32 s82, 0x100
	s_cselect_b32 s98, 1, 0
	s_cmp_eq_u32 s99, 1
	s_cselect_b32 s98, s98, 0
	s_waitcnt vmcnt(0)
	s_waitcnt vmcnt(0) lgkmcnt(0)
	s_barrier
	s_mov_b64 s[2:3], exec
	v_readlane_b32 s4, v254, 1
	v_readlane_b32 s5, v254, 2
	s_and_b64 s[4:5], s[2:3], s[4:5]
	s_mov_b64 exec, s[4:5]
	s_cbranch_execz .LBB0_752
	v_readlane_b32 s4, v254, 22
	s_waitcnt vmcnt(0) expcnt(0) lgkmcnt(0)
	s_nop 0
	v_mov_b32_e32 v0, s4
	ds_read_b32 v2, v0
	ds_read_b32 v0, v0 offset:4
	s_waitcnt lgkmcnt(1)
	v_cmp_ne_u32_e32 vcc, 0, v2
	s_cbranch_vccnz .LBB0_720
	v_readlane_b32 s4, v254, 0
	s_mul_i32 s33, s83, s4
	s_add_u32 s4, s88, 0xffc0200
	s_addc_u32 s5, s89, 0
	s_add_u32 s8, s88, 0xffc0400
	s_addc_u32 s9, s89, 0
	s_add_u32 s10, s88, 0xffc0500
	s_addc_u32 s11, s89, 0
	s_add_u32 s12, s88, 0xffc0600
	s_addc_u32 s13, s89, 0
	s_add_u32 s14, s88, 0xffc0700
	s_addc_u32 s15, s89, 0
	s_add_u32 s16, s88, 0xffc0800
	s_addc_u32 s17, s89, 0
	s_add_u32 s18, s88, 0xffc0900
	s_addc_u32 s19, s89, 0
	s_add_u32 s20, s88, 0xffc0a00
	s_addc_u32 s21, s89, 0
	s_add_u32 s22, s88, 0xffc0b00
	s_addc_u32 s23, s89, 0
	s_add_u32 s24, s88, 0xffc0c00
	s_addc_u32 s25, s89, 0
	s_add_u32 s26, s88, 0xffc0d00
	s_addc_u32 s27, s89, 0
	s_add_u32 s28, s88, 0xffc0e00
	s_addc_u32 s29, s89, 0
	s_add_u32 s30, s88, 0xffc0f00
	s_addc_u32 s31, s89, 0
	s_add_u32 s34, s88, 0xffc1000
	s_addc_u32 s35, s89, 0
	s_add_u32 s36, s88, 0xffc1100
	s_addc_u32 s37, s89, 0
	s_add_u32 s38, s88, 0xffc1200
	s_addc_u32 s39, s89, 0
	s_add_u32 s40, s88, 0xffc1300
	s_mul_i32 s33, s33, s82
	s_addc_u32 s41, s89, 0
	s_mov_b32 s48, 1
	v_mov_b32_e32 v16, 0
	s_branch .LBB0_708
